# XCD-local barrier fast path at 3 seams per layer (PF-PG, PH2-PI, PJ-PK) guarded by runtime placement check; PC ushort loads hoisted; L1 inv hoisted
# speedup vs baseline: 1.0164x; 1.0164x over previous
; #define LAS __attribute__((address_space(3)))
; __device__ __forceinline__ unsigned xb_add(unsigned* p, unsigned v) { return __hip_atomic_fetch_add(p, v, __ATOMIC_RELAXED, __HIP_MEMORY_SCOPE_AGENT); }
; __device__ __forceinline__ unsigned xb_xcc_id() { return (unsigned)__builtin_amdgcn_s_getreg((3 << 11) | 20) & 0xFu; }
; __device__ __forceinline__ XcdBarrier xcd_barrier_post(unsigned* bar, volatile LAS unsigned* st) {
;     XcdBarrier b; b.bar = bar; b.x = xb_xcc_id(); b.st = st;
;     if (threadIdx.x == 0) (void)xb_add(&bar[XB_XCNT(b.x)], 1u);
;     return b;
; }
; __global__ void __launch_bounds__(NWAVES * 64, 2) fwd_kernel(KArgs a) {
;     ...
;     if (threadIdx.x < 2) ((volatile LAS unsigned*)(lds + XBST_OFF))[threadIdx.x] = 0u;
;     __syncthreads();
;     XcdBarrier xbar = xcd_barrier_post((unsigned*)(a.ws + WS_BAR), (volatile LAS unsigned*)(lds + XBST_OFF));
.LBB0_3:
	s_or_b64 exec, exec, s[2:3]
	s_load_dwordx2 s[2:3], s[0:1], 0x110
	s_waitcnt lgkmcnt(0)
	s_barrier
	s_getreg_b32 s4, hwreg(HW_REG_XCC_ID, 0, 4)
	s_add_u32 s6, s2, 0xc0000
	s_addc_u32 s7, s3, 0
	v_writelane_b32 v254, s6, 1
	s_and_b32 s4, s4, 15
	v_mov_b64_e32 v[34:35], s[2:3]
	v_writelane_b32 v254, s7, 2
	v_writelane_b32 v254, s4, 3
	v_cmp_eq_u32_e64 s[6:7], 0, v1
	s_mov_b64 s[4:5], exec
	s_nop 0
	v_writelane_b32 v254, s6, 4
	s_nop 1
	v_writelane_b32 v254, s7, 5
	s_and_b64 s[6:7], s[4:5], s[6:7]
	s_mov_b64 exec, s[6:7]
	s_cbranch_execz .LBB0_7
	s_mov_b64 s[8:9], exec
	v_mbcnt_lo_u32_b32 v2, s8, 0
	v_mbcnt_hi_u32_b32 v2, s9, v2
	v_cmp_eq_u32_e32 vcc, 0, v2
	s_and_saveexec_b64 s[6:7], vcc
	s_cbranch_execz .LBB0_6
	v_readlane_b32 s11, v254, 3
	s_bcnt1_i32_b64 s8, s[8:9]
	s_lshl_b32 s11, s11, 8
	v_mov_b32_e32 v3, s8
	v_readlane_b32 s8, v254, 1
	v_mov_b32_e32 v2, s11
	v_readlane_b32 s9, v254, 2
	s_nop 4
	global_atomic_add v2, v3, s[8:9] offset:1024
	v_readlane_b32 s100, v254, 0
	v_readlane_b32 s101, v254, 3
	s_nop 3
	s_and_b32 s100, s100, 7
	s_lshl_b32 s100, s100, 6
	s_lshl_b32 s101, 1, s101
	v_mov_b32_e32 v2, s100
	v_mov_b32_e32 v3, s101
	global_atomic_or v2, v3, s[8:9]

; #define LAS __attribute__((address_space(3)))
; __device__ __forceinline__ int lane_id_asm() { int l; asm volatile("v_mbcnt_lo_u32_b32 %0, -1, 0\n\tv_mbcnt_hi_u32_b32 %0, -1, %0" : "=v"(l)); return l; }
; __global__ void __launch_bounds__(NWAVES * 64, 2) fwd_kernel(KArgs a) {
;     ...
;             if (l == 0) {
;                 const int first = (G > 96) ? 96 : 0, nb = G - first;
;                 if ((int)blockIdx.x >= first) {
;                     const int ln5 = lane_id_asm(); LAS float* scr = (LAS float*)(lds + wave * 16384);
;                     for (int d = ((int)blockIdx.x - first) * NWAVES + wave; d < CI_DSPLIT; d += nb * NWAVES) convert_deferred(lds, ws, d, scr, ln5);
;     ...
;             if (l == 0) {
;                 const int first = (G > 128) ? 128 : 0, nb = G - first;
;                 if ((int)blockIdx.x >= first) {
;                     const int ln5 = lane_id_asm(); LAS float* scr = (LAS float*)(lds + wave * 16384);
;                     for (int d = CI_DSPLIT + ((int)blockIdx.x - first) * NWAVES + wave; d < CI_DTOT; d += nb * NWAVES) convert_deferred(lds, ws, d, scr, ln5);
;                 }
.LBB0_139:
	s_or_b64 exec, exec, s[0:1]
	s_and_b32 s10, s50, 0xffffffc0
	s_ashr_i32 s93, s44, 31
	s_cmpk_gt_i32 s44, 0x60
	s_cselect_b32 s1, 0x60, 0
	s_sub_i32 s4, s44, s1
	v_readlane_b32 s9, v254, 0
	s_cmp_ge_i32 s9, s1
	s_cselect_b64 s[6:7], -1, 0
	s_sub_i32 s5, s9, s1
	v_writelane_b32 v254, s6, 7
	s_lshl_b32 s5, s5, 3
	s_mul_i32 s0, s45, s44
	v_writelane_b32 v254, s7, 8
	s_add_i32 s6, s5, s52
	s_cmpk_lt_i32 s6, 0x1c38
	s_cselect_b64 s[14:15], -1, 0
	v_writelane_b32 v254, s14, 9
	s_lshl_b32 s4, s4, 3
	s_mul_i32 s91, s0, s51
	v_writelane_b32 v254, s15, 10
	v_writelane_b32 v254, s4, 11
	s_add_u32 s4, s2, 0xc0200
	s_addc_u32 s5, s3, 0
	v_writelane_b32 v254, s4, 12
	s_waitcnt lgkmcnt(0)
	v_mbcnt_hi_u32_b32 v0, -1, v43
	s_mov_b32 s97, 0
	v_writelane_b32 v254, s5, 13
	s_add_u32 s4, s2, 0xc0400
	s_addc_u32 s5, s3, 0
	v_writelane_b32 v254, s4, 14
	v_mov_b32_e32 v157, 0
	v_mov_b32_e32 v212, 0x358637bd
	v_writelane_b32 v254, s5, 15
	s_add_u32 s4, s2, 0xc0500
	s_addc_u32 s5, s3, 0
	v_writelane_b32 v254, s4, 16
	v_mov_b32_e32 v213, 1
	v_and_b32_e32 v214, 32, v0
	v_writelane_b32 v254, s5, 17
	s_add_u32 s4, s2, 0xc0600
	s_addc_u32 s5, s3, 0
	v_writelane_b32 v254, s4, 18
	v_mov_b64_e32 v[160:161], 0x100
	v_mov_b64_e32 v[162:163], 0xff
	v_writelane_b32 v254, s5, 19
	s_add_u32 s4, s2, 0xc0700
	s_addc_u32 s5, s3, 0
	v_writelane_b32 v254, s4, 20
	v_mov_b64_e32 v[164:165], 0x57f
	s_movk_i32 s53, 0x2400
	v_writelane_b32 v254, s5, 21
	s_add_u32 s4, s2, 0xc0800
	s_addc_u32 s5, s3, 0
	s_add_u32 s74, s2, 0xc0900
	s_addc_u32 s75, s3, 0
	s_add_u32 s76, s2, 0xc0a00
	s_addc_u32 s77, s3, 0
	s_add_u32 s78, s2, 0xc0b00
	s_addc_u32 s79, s3, 0
	s_add_u32 s80, s2, 0xc0c00
	s_addc_u32 s81, s3, 0
	s_add_u32 s82, s2, 0xc0d00
	s_addc_u32 s83, s3, 0
	s_add_u32 s84, s2, 0xc0e00
	s_addc_u32 s85, s3, 0
	s_add_u32 s64, s2, 0xc0f00
	s_addc_u32 s65, s3, 0
	s_add_u32 s66, s2, 0xc1000
	s_addc_u32 s67, s3, 0
	s_add_u32 s68, s2, 0xc1100
	s_addc_u32 s69, s3, 0
	s_add_u32 s70, s2, 0xc1200
	s_addc_u32 s71, s3, 0
	s_add_u32 s72, s2, 0xc1300
	v_writelane_b32 v254, s4, 22
	s_addc_u32 s73, s3, 0
	s_movk_i32 s86, 0x1600
	v_writelane_b32 v254, s5, 23
	s_add_u32 s4, s2, 0xc3400
	s_addc_u32 s5, s3, 0
	s_add_u32 s2, s2, 0xc3500
	v_writelane_b32 v254, s4, 24
	s_addc_u32 s3, s3, 0
	s_cmpk_gt_i32 s44, 0x80
	v_writelane_b32 v254, s5, 25
	v_writelane_b32 v254, s2, 26
	s_cselect_b32 s0, 0x80, 0
	s_mov_b32 s87, 0xc2080000
	v_writelane_b32 v254, s3, 27
	s_sub_i32 s2, s44, s0
	s_cmp_ge_i32 s9, s0
	s_cselect_b64 s[4:5], -1, 0
	s_sub_i32 s3, s9, s0
	s_lshl_b32 s3, s3, 3
	s_add_i32 s3, s52, s3
	s_add_i32 s11, s3, 0x1c38
	v_writelane_b32 v254, s4, 28
	s_cmpk_lt_i32 s11, 0x3240
	s_mov_b32 s45, 0xff61b1e6
	v_writelane_b32 v254, s5, 29
	s_cselect_b64 s[4:5], -1, 0
	v_writelane_b32 v254, s4, 30
	s_lshl_b32 s20, s2, 3
	s_lshl_b32 s2, s9, 8
	s_lshl_b32 s3, s1, 8
	v_writelane_b32 v254, s5, 31
	s_sub_i32 s4, s2, s3
	s_lshl_b32 s14, s44, 8
	v_writelane_b32 v254, s4, 32
	s_sub_i32 s3, s14, s3
	v_writelane_b32 v254, s3, 33
	s_lshl_b32 s3, s9, 4
	s_lshl_b32 s4, s52, 1
	s_add_i32 s3, s3, s4
	s_lshl_b32 s4, s1, 4
	s_sub_i32 s5, s3, s4
	s_add_i32 s5, s5, 0x1c940
	v_writelane_b32 v254, s5, 34
	s_lshl_b32 s5, s44, 4
	s_sub_i32 s4, s5, s4
	v_writelane_b32 v254, s4, 35
	s_lshl_b32 s4, s6, 6
	v_writelane_b32 v254, s4, 36
	s_lshl_b32 s4, s1, 9
	s_sub_i32 s4, s12, s4
	v_writelane_b32 v254, s4, 37
	v_writelane_b32 v254, s6, 38
	s_lshl_b32 s4, s6, 4
	v_writelane_b32 v254, s4, 39
	s_lshl_b32 s4, s44, 7
	s_lshl_b32 s6, s1, 7
	s_sub_i32 s6, s4, s6
	v_writelane_b32 v254, s6, 40
	s_lshl_b32 s6, s9, 5
	s_lshl_b32 s7, s52, 2
	s_add_i32 s6, s6, s7
	s_lshl_b32 s7, s1, 5
	s_sub_i32 s8, s6, s7
	s_addk_i32 s8, 0x6780
	s_lshl_b32 s15, s44, 5
	v_writelane_b32 v254, s8, 41
	s_sub_i32 s7, s15, s7
	v_writelane_b32 v254, s7, 42
	s_lshl_b32 s7, s9, 3
	s_add_i32 s7, s52, s7
	s_lshl_b32 s8, s1, 3
	s_sub_i32 s8, s7, s8
	s_lshl_b32 s8, s8, 3
	s_add_i32 s8, s8, 0xc800
	v_writelane_b32 v254, s8, 43
	s_lshl_b32 s8, s44, 6
	s_lshl_b32 s1, s1, 6
	s_sub_i32 s1, s8, s1
	v_writelane_b32 v254, s1, 44
	v_writelane_b32 v254, s10, 45
	s_add_i32 s1, s10, 0xfffffe00
	v_writelane_b32 v254, s1, 46
	s_lshl_b32 s1, s52, 10
	s_add_i32 s1, s1, 0
	v_writelane_b32 v254, s1, 47
	s_lshl_b32 s1, s0, 4
	s_sub_i32 s3, s3, s1
	s_add_i32 s3, s3, 0x215b0
	s_lshl_b32 s13, s52, 5
	v_writelane_b32 v254, s3, 48
	s_sub_i32 s1, s5, s1
	v_writelane_b32 v254, s1, 49
	s_add_i32 s2, s2, s13
	s_lshl_b32 s1, s0, 8
	v_writelane_b32 v254, s13, 50
	s_sub_i32 s2, s2, s1
	v_writelane_b32 v254, s2, 51
	v_writelane_b32 v254, s14, 52
	s_sub_i32 s1, s14, s1
	v_writelane_b32 v254, s1, 53
	s_lshl_b32 s1, s11, 6
	v_writelane_b32 v254, s1, 54
	s_lshl_b32 s1, s0, 9
	s_sub_i32 s1, s12, s1
	v_writelane_b32 v254, s1, 55
	v_writelane_b32 v254, s11, 56
	s_lshl_b32 s1, s11, 4
	v_writelane_b32 v254, s1, 57
; #define LAS __attribute__((address_space(3)))
; #define GASP __attribute__((address_space(1)))
; __device__ __forceinline__ unsigned char* argp(LAS unsigned char* lds, int i) {
;     unsigned addr = (unsigned)(uintptr_t)(lds + ARGS_OFF) + 8u * (unsigned)i; asm volatile("" : "+s"(addr));
;     const unsigned long long v = *(volatile LAS unsigned long long*)(uintptr_t)addr;
;     const unsigned lo = __builtin_amdgcn_readfirstlane((unsigned)v), hi = __builtin_amdgcn_readfirstlane((unsigned)(v >> 32));
;     return (unsigned char*)(GASP unsigned char*)(((unsigned long long)hi << 32) | lo);
; }
	s_lshl_b32 s1, s0, 7
	s_sub_i32 s1, s4, s1
	v_writelane_b32 v254, s1, 58
	s_lshl_b32 s1, s0, 5
	s_sub_i32 s2, s6, s1
	s_add_i32 s2, s2, 0xd860
	v_writelane_b32 v254, s2, 59
	v_writelane_b32 v254, s15, 60
	s_sub_i32 s1, s15, s1
	v_writelane_b32 v254, s1, 61
	s_lshl_b32 s1, s0, 3
	s_sub_i32 s1, s7, s1
	s_lshl_b32 s1, s1, 3
	s_add_i32 s1, s1, 0x1a9c0
	s_lshl_b32 s0, s0, 6
	v_writelane_b32 v254, s1, 62
	s_sub_i32 s0, s8, s0
	v_writelane_b32 v254, s0, 63
	s_add_i32 s0, 0, 0x20510
	v_writelane_b32 v215, s0, 0
	s_add_i32 s0, 0, 0x20420
	v_writelane_b32 v215, s0, 1
	s_add_i32 s0, 0, 0x20428
	v_writelane_b32 v215, s0, 2
	s_add_i32 s0, 0, 0x204a8
	v_writelane_b32 v215, s0, 3
	s_add_i32 s0, 0, 0x204a0
	v_writelane_b32 v215, s0, 4
	s_add_i32 s0, 0, 0x20418
	v_writelane_b32 v215, s0, 5
	s_add_i32 s0, 0, 0x20410
	v_writelane_b32 v215, s0, 6
	s_add_i32 s0, 0, 0x20500
	v_writelane_b32 v215, s0, 7
	s_add_i32 s0, 0, 0x204f8
	v_writelane_b32 v215, s0, 8
	s_add_i32 s0, 0, 0x204f0
	v_writelane_b32 v215, s0, 9
	s_add_i32 s0, 0, 0x20498
	v_writelane_b32 v215, s0, 10
	s_add_i32 s0, 0, 0x20450
	v_writelane_b32 v215, s0, 11
	s_add_i32 s0, 0, 0x204e8
	v_writelane_b32 v215, s0, 12
	s_add_i32 s0, 0, 0x204c0
	v_writelane_b32 v215, s0, 13
	s_add_i32 s0, 0, 0x204b0
	v_writelane_b32 v215, s0, 14
	s_add_i32 s0, 0, 0x20200
	v_writelane_b32 v215, s0, 15
	s_add_i32 s0, 0, 0x20204
	v_writelane_b32 v215, s0, 16
	s_add_i32 s0, 0, 0x20430
	v_writelane_b32 v215, s0, 17
	s_add_i32 s0, 0, 0x20438
	v_writelane_b32 v215, s0, 18
	s_add_i32 s0, 0, 0x20440
	v_writelane_b32 v215, s0, 19
	s_add_i32 s0, 0, 0x20448
	v_writelane_b32 v215, s0, 20
	s_add_i32 s0, 0, 0x20458
	v_writelane_b32 v215, s0, 21
	s_add_i32 s0, 0, 0x20460
	v_writelane_b32 v215, s0, 22
	s_add_i32 s0, 0, 0x20468
	v_writelane_b32 v215, s0, 23
	s_add_i32 s0, 0, 0x20470
	v_writelane_b32 v215, s0, 24
	s_add_i32 s0, 0, 0x20478
	v_writelane_b32 v215, s0, 25
	s_add_i32 s0, 0, 0x20480
	v_writelane_b32 v215, s0, 26
	s_add_i32 s0, 0, 0x20488
	v_writelane_b32 v215, s0, 27
	s_add_i32 s0, 0, 0x20490
	v_writelane_b32 v215, s0, 28
	s_add_i32 s0, 0, 0x204d0
	v_writelane_b32 v215, s0, 29
	s_add_i32 s0, 0, 0x204b8
	v_writelane_b32 v215, s0, 30
	s_add_i32 s0, 0, 0x204c8
	v_writelane_b32 v215, s0, 31
	s_add_i32 s96, 0, 0x20508
	s_mov_b64 s[0:1], -1
	v_writelane_b32 v215, s0, 32
	s_add_i32 s10, 0, 0x204e0
	s_movk_i32 s52, 0x7fff
	v_writelane_b32 v215, s1, 33
	v_writelane_b32 v215, s91, 34
	v_writelane_b32 v215, s96, 35
	v_writelane_b32 v215, s20, 36
	s_add_i32 s11, 0, 0x204d8
	s_mov_b64 s[94:95], 0x80
	s_mov_b64 s[50:51], 0x2000
	s_mov_b32 s6, s97
	v_writelane_b32 v215, s10, 37
	s_barrier
	v_writelane_b32 v215, s11, 38
	v_readlane_b32 s100, v254, 1
	v_readlane_b32 s101, v254, 2
	v_mov_b32_e32 v0, 0
	v_mov_b32_e32 v10, s44
	s_nop 4
	global_load_dword v1, v0, s[100:101] sc1
	global_load_dword v2, v0, s[100:101] offset:64 sc1
	global_load_dword v3, v0, s[100:101] offset:128 sc1
	global_load_dword v4, v0, s[100:101] offset:192 sc1
	global_load_dword v5, v0, s[100:101] offset:256 sc1
	global_load_dword v6, v0, s[100:101] offset:320 sc1
	global_load_dword v7, v0, s[100:101] offset:384 sc1
	global_load_dword v8, v0, s[100:101] offset:448 sc1
	v_xor_b32_e32 v10, 0x100, v10
	s_waitcnt vmcnt(0)
	v_add_u32_e32 v9, -1, v1
	v_and_b32_e32 v9, v9, v1
	v_or_b32_e32 v10, v10, v9
	v_cmp_eq_u32_e32 vcc, 0, v1
	s_nop 1
	v_cndmask_b32_e64 v9, 0, 1, vcc
	v_or_b32_e32 v10, v10, v9
	v_add_u32_e32 v9, -1, v2
	v_and_b32_e32 v9, v9, v2
	v_or_b32_e32 v10, v10, v9
	v_cmp_eq_u32_e32 vcc, 0, v2
	s_nop 1
	v_cndmask_b32_e64 v9, 0, 1, vcc
	v_or_b32_e32 v10, v10, v9
	v_add_u32_e32 v9, -1, v3
	v_and_b32_e32 v9, v9, v3
	v_or_b32_e32 v10, v10, v9
	v_cmp_eq_u32_e32 vcc, 0, v3
	s_nop 1
	v_cndmask_b32_e64 v9, 0, 1, vcc
	v_or_b32_e32 v10, v10, v9
	v_add_u32_e32 v9, -1, v4
	v_and_b32_e32 v9, v9, v4
	v_or_b32_e32 v10, v10, v9
	v_cmp_eq_u32_e32 vcc, 0, v4
	s_nop 1
	v_cndmask_b32_e64 v9, 0, 1, vcc
	v_or_b32_e32 v10, v10, v9
	v_add_u32_e32 v9, -1, v5
	v_and_b32_e32 v9, v9, v5
	v_or_b32_e32 v10, v10, v9
	v_cmp_eq_u32_e32 vcc, 0, v5
	s_nop 1
	v_cndmask_b32_e64 v9, 0, 1, vcc
	v_or_b32_e32 v10, v10, v9
	v_add_u32_e32 v9, -1, v6
	v_and_b32_e32 v9, v9, v6
	v_or_b32_e32 v10, v10, v9
	v_cmp_eq_u32_e32 vcc, 0, v6
	s_nop 1
	v_cndmask_b32_e64 v9, 0, 1, vcc
	v_or_b32_e32 v10, v10, v9
	v_add_u32_e32 v9, -1, v7
	v_and_b32_e32 v9, v9, v7
	v_or_b32_e32 v10, v10, v9
	v_cmp_eq_u32_e32 vcc, 0, v7
	s_nop 1
	v_cndmask_b32_e64 v9, 0, 1, vcc
	v_or_b32_e32 v10, v10, v9
	v_add_u32_e32 v9, -1, v8
	v_and_b32_e32 v9, v9, v8
	v_or_b32_e32 v10, v10, v9
	v_cmp_eq_u32_e32 vcc, 0, v8
	s_nop 1
	v_cndmask_b32_e64 v9, 0, 1, vcc
	v_or_b32_e32 v10, v10, v9
	v_cmp_eq_u32_e32 vcc, 0, v10
	s_nop 1
	v_cndmask_b32_e64 v9, 0, 1, vcc
	v_mov_b32_e32 v11, 0x20208
	ds_write_b32 v11, v9
	s_waitcnt lgkmcnt(0)
	s_branch .LBB0_143

; #define LAS __attribute__((address_space(3)))
; __device__ __forceinline__ unsigned cvt_pk_bf16(float lo, float hi) { f32x2 v = {lo, hi}; bf16x2_t b = __builtin_convertvector(v, bf16x2_t); return __builtin_bit_cast(unsigned, b); }
; #define MFMA16(a, b, c) __builtin_amdgcn_mfma_f32_16x16x32_bf16((a), (b), (c), 0, 0, 0)
; template <bool PASSC>
; __device__ __forceinline__ void ssm_task(int task, const SsmW& W, const bf16_t* U, f32x2* SST, bf16_t* YS, LAS unsigned char* wl, int lane) {
;     ...
;         const bf16_t* ub = U + (tok0 + blk * 16) * 256 + g * 16;
;         bf16x8 af = zfrag;
;         if (kq < 2) af = *(const bf16x8*)(ub + (size_t)hh * 256 + kq * 8);
; #pragma unroll
;         for (int nb = 0; nb < 8; ++nb) {
;             const f32x4 d = MFMA16(af, bfr[nb], ((f32x4){0.f, 0.f, 0.f, 0.f}));
; #pragma unroll
;             for (int i = 0; i < 4; ++i) *(LAS float*)(BU + (4 * kq + i) * 520 + (16 * nb + hh) * 4) = d[i];
;         }
;         asm volatile("s_waitcnt lgkmcnt(0)" ::: "memory");
; #pragma unroll
;         for (int s = 0; s < 16; ++s) {
;             const f32x2 bu = *(const LAS f32x2*)(BU + s * 520 + 8 * lane);
;             const float nr = ar * xr - ai * xi + bu.x, ni = ar * xi + ai * xr + bu.y; xr = nr; xi = ni;
;             if (PASSC) *(LAS unsigned*)(xb + s * 272 + 4 * lane) = cvt_pk_bf16(xr, xi);
;         }
.LBB0_549:
	s_or_b64 exec, exec, s[6:7]
	s_waitcnt vmcnt(0) lgkmcnt(0)
	s_mov_b64 s[100:101], 0x9800000
	v_lshl_add_u64 v[96:97], v[58:59], 0, s[4:5]
	v_lshl_add_u64 v[96:97], v[96:97], 0, s[100:101]
	global_load_ushort v92, v[96:97], off
	global_load_ushort v93, v[96:97], off offset:512
	global_load_ushort v94, v[96:97], off offset:1024
	global_load_ushort v95, v[96:97], off offset:1536
	v_mfma_f32_16x16x32_bf16 v[84:87], v[48:51], v[4:7], 0
	v_add_u32_e32 v61, 0x400, v120
	s_mov_b32 s6, 0x9800000
	v_mfma_f32_16x16x32_bf16 v[88:91], v[48:51], v[0:3], 0
	s_nop 7
	ds_write2_b32 v119, v84, v88 offset1:16
	ds_write2_b32 v120, v85, v89 offset1:16
	ds_write2_b32 v120, v86, v90 offset0:130 offset1:146
	ds_write2_b32 v61, v87, v91 offset0:4 offset1:20
	v_mfma_f32_16x16x32_bf16 v[84:87], v[48:51], v[12:15], 0
	v_mfma_f32_16x16x32_bf16 v[88:91], v[48:51], v[8:11], 0
	s_nop 7
	ds_write2_b32 v119, v84, v88 offset0:32 offset1:48
	ds_write2_b32 v120, v85, v89 offset0:32 offset1:48
	ds_write2_b32 v120, v86, v90 offset0:162 offset1:178
	ds_write2_b32 v61, v87, v91 offset0:36 offset1:52
	v_mfma_f32_16x16x32_bf16 v[84:87], v[48:51], v[20:23], 0
	v_mfma_f32_16x16x32_bf16 v[88:91], v[48:51], v[16:19], 0
	s_nop 7
	ds_write2_b32 v119, v84, v88 offset0:64 offset1:80
	ds_write2_b32 v120, v85, v89 offset0:64 offset1:80
	ds_write2_b32 v120, v86, v90 offset0:194 offset1:210
	ds_write2_b32 v61, v87, v91 offset0:68 offset1:84
	v_mfma_f32_16x16x32_bf16 v[84:87], v[48:51], v[28:31], 0
	v_mfma_f32_16x16x32_bf16 v[48:51], v[48:51], v[24:27], 0
	s_nop 7
	ds_write2_b32 v119, v84, v48 offset0:96 offset1:112
	ds_write2_b32 v120, v85, v49 offset0:96 offset1:112
	ds_write2_b32 v120, v86, v50 offset0:226 offset1:242
	ds_write2_b32 v61, v87, v51 offset0:100 offset1:116
	s_waitcnt lgkmcnt(0)
	ds_read_b64 v[48:49], v121
	v_pk_mul_f32 v[50:51], v[54:55], v[82:83] op_sel_hi:[1,0]
	s_nop 0
	v_pk_fma_f32 v[62:63], v[76:77], v[80:81], v[50:51] neg_lo:[0,0,1] neg_hi:[0,0,1]
	v_pk_fma_f32 v[50:51], v[76:77], v[80:81], v[50:51] op_sel_hi:[1,0,1]
	s_nop 0
	v_mov_b32_e32 v63, v51
	s_waitcnt lgkmcnt(0)
	v_pk_add_f32 v[48:49], v[62:63], v[48:49]
	s_nop 0
	v_cvt_pk_bf16_f32 v50, v48, v49
	ds_write_b32 v122, v50 offset:8320
	ds_read_b64 v[50:51], v121 offset:520
	v_pk_mul_f32 v[62:63], v[78:79], v[48:49]
	s_nop 0
	v_pk_fma_f32 v[80:81], v[52:53], v[48:49], v[62:63] op_sel:[0,0,1] op_sel_hi:[1,1,0] neg_lo:[0,0,1] neg_hi:[0,0,1]
	v_pk_fma_f32 v[48:49], v[52:53], v[48:49], v[62:63] op_sel:[0,0,1] op_sel_hi:[1,1,0]
	s_nop 0
	v_mov_b32_e32 v81, v49
	s_waitcnt lgkmcnt(0)
	v_pk_add_f32 v[48:49], v[50:51], v[80:81]
	s_nop 0
	v_cvt_pk_bf16_f32 v50, v48, v49
	ds_write_b32 v122, v50 offset:8592
	ds_read_b64 v[50:51], v121 offset:1040
	v_pk_mul_f32 v[62:63], v[78:79], v[48:49]
	s_nop 0
	v_pk_fma_f32 v[80:81], v[52:53], v[48:49], v[62:63] op_sel:[0,0,1] op_sel_hi:[1,1,0] neg_lo:[0,0,1] neg_hi:[0,0,1]
	v_pk_fma_f32 v[48:49], v[52:53], v[48:49], v[62:63] op_sel:[0,0,1] op_sel_hi:[1,1,0]
	s_nop 0
	v_mov_b32_e32 v81, v49
	s_waitcnt lgkmcnt(0)
	v_pk_add_f32 v[48:49], v[50:51], v[80:81]
	s_nop 0
	v_cvt_pk_bf16_f32 v50, v48, v49
	ds_write_b32 v122, v50 offset:8864
	ds_read_b64 v[50:51], v121 offset:1560
	v_pk_mul_f32 v[62:63], v[78:79], v[48:49]
	s_nop 0
	v_pk_fma_f32 v[80:81], v[52:53], v[48:49], v[62:63] op_sel:[0,0,1] op_sel_hi:[1,1,0] neg_lo:[0,0,1] neg_hi:[0,0,1]
	v_pk_fma_f32 v[48:49], v[52:53], v[48:49], v[62:63] op_sel:[0,0,1] op_sel_hi:[1,1,0]
	s_nop 0
	v_mov_b32_e32 v81, v49
	s_waitcnt lgkmcnt(0)
	v_pk_add_f32 v[48:49], v[50:51], v[80:81]
	s_nop 0
	v_cvt_pk_bf16_f32 v50, v48, v49
	ds_write_b32 v122, v50 offset:9136
	ds_read_b64 v[50:51], v121 offset:2080
	v_pk_mul_f32 v[62:63], v[78:79], v[48:49]
	s_nop 0
	v_pk_fma_f32 v[80:81], v[52:53], v[48:49], v[62:63] op_sel:[0,0,1] op_sel_hi:[1,1,0] neg_lo:[0,0,1] neg_hi:[0,0,1]
	v_pk_fma_f32 v[48:49], v[52:53], v[48:49], v[62:63] op_sel:[0,0,1] op_sel_hi:[1,1,0]
	s_nop 0
	v_mov_b32_e32 v81, v49
	s_waitcnt lgkmcnt(0)
	v_pk_add_f32 v[48:49], v[50:51], v[80:81]
	s_nop 0
	v_cvt_pk_bf16_f32 v50, v48, v49
	ds_write_b32 v122, v50 offset:9408
	ds_read_b64 v[50:51], v121 offset:2600
	v_pk_mul_f32 v[62:63], v[78:79], v[48:49]
	s_nop 0
	v_pk_fma_f32 v[80:81], v[52:53], v[48:49], v[62:63] op_sel:[0,0,1] op_sel_hi:[1,1,0] neg_lo:[0,0,1] neg_hi:[0,0,1]
	v_pk_fma_f32 v[48:49], v[52:53], v[48:49], v[62:63] op_sel:[0,0,1] op_sel_hi:[1,1,0]
	s_nop 0
	v_mov_b32_e32 v81, v49
	s_waitcnt lgkmcnt(0)
	v_pk_add_f32 v[48:49], v[50:51], v[80:81]
	s_nop 0
	v_cvt_pk_bf16_f32 v50, v48, v49
	ds_write_b32 v122, v50 offset:9680
	ds_read_b64 v[50:51], v121 offset:3120
	v_pk_mul_f32 v[62:63], v[78:79], v[48:49]
	s_nop 0
	v_pk_fma_f32 v[80:81], v[52:53], v[48:49], v[62:63] op_sel:[0,0,1] op_sel_hi:[1,1,0] neg_lo:[0,0,1] neg_hi:[0,0,1]
	v_pk_fma_f32 v[48:49], v[52:53], v[48:49], v[62:63] op_sel:[0,0,1] op_sel_hi:[1,1,0]
	s_nop 0
	v_mov_b32_e32 v81, v49
	s_waitcnt lgkmcnt(0)
	v_pk_add_f32 v[48:49], v[50:51], v[80:81]
	s_nop 0
	v_cvt_pk_bf16_f32 v50, v48, v49
	ds_write_b32 v122, v50 offset:9952
	ds_read_b64 v[50:51], v121 offset:3640
	v_pk_mul_f32 v[62:63], v[78:79], v[48:49]
	s_nop 0
	v_pk_fma_f32 v[80:81], v[52:53], v[48:49], v[62:63] op_sel:[0,0,1] op_sel_hi:[1,1,0] neg_lo:[0,0,1] neg_hi:[0,0,1]
	v_pk_fma_f32 v[48:49], v[52:53], v[48:49], v[62:63] op_sel:[0,0,1] op_sel_hi:[1,1,0]
	s_nop 0
	v_mov_b32_e32 v81, v49
	s_waitcnt lgkmcnt(0)
; #define LAS __attribute__((address_space(3)))
; __device__ __forceinline__ unsigned cvt_pk_bf16(float lo, float hi) { f32x2 v = {lo, hi}; bf16x2_t b = __builtin_convertvector(v, bf16x2_t); return __builtin_bit_cast(unsigned, b); }
; __device__ __forceinline__ bf16_t f2bf(float f) { unsigned u = __builtin_bit_cast(unsigned, f); return (bf16_t)((u + 0x7fffu + ((u >> 16) & 1u)) >> 16); }
; #define MFMA16(a, b, c) __builtin_amdgcn_mfma_f32_16x16x32_bf16((a), (b), (c), 0, 0, 0)
; template <bool PASSC>
; __device__ __forceinline__ void ssm_task(int task, const SsmW& W, const bf16_t* U, f32x2* SST, bf16_t* YS, LAS unsigned char* wl, int lane) {
;     ...
;         asm volatile("s_waitcnt lgkmcnt(0)" ::: "memory");
; #pragma unroll
;         for (int s = 0; s < 16; ++s) {
;             const f32x2 bu = *(const LAS f32x2*)(BU + s * 520 + 8 * lane);
;             const float nr = ar * xr - ai * xi + bu.x, ni = ar * xi + ai * xr + bu.y; xr = nr; xi = ni;
;             if (PASSC) *(LAS unsigned*)(xb + s * 272 + 4 * lane) = cvt_pk_bf16(xr, xi);
;         }
;         if (PASSC) {
;             asm volatile("s_waitcnt lgkmcnt(0)" ::: "memory");
;             f32x4 y = (f32x4){0.f, 0.f, 0.f, 0.f};
; #pragma unroll
;             for (int ks = 0; ks < 4; ++ks) { const bf16x8 a0 = *(const LAS bf16x8*)(xb + hh * 272 + 64 * ks + 16 * kq); y = MFMA16(a0, cf[ks], y); }
; #pragma unroll
;             for (int i = 0; i < 4; ++i) {
;                 const size_t e = (size_t)(4 * kq + i) * 256 + hh;
;                 YS[(tok0 + blk * 16) * 256 + g * 16 + e] = f2bf(y[i] + dk * bf2f(ub[e]));
;             }
;         }
;         asm volatile("s_waitcnt lgkmcnt(0)" ::: "memory");
	v_pk_add_f32 v[48:49], v[50:51], v[80:81]
	s_nop 0
	v_cvt_pk_bf16_f32 v50, v48, v49
	ds_write_b32 v122, v50 offset:10224
	ds_read_b64 v[50:51], v121 offset:4160
	v_pk_mul_f32 v[62:63], v[78:79], v[48:49]
	s_nop 0
	v_pk_fma_f32 v[80:81], v[52:53], v[48:49], v[62:63] op_sel:[0,0,1] op_sel_hi:[1,1,0] neg_lo:[0,0,1] neg_hi:[0,0,1]
	v_pk_fma_f32 v[48:49], v[52:53], v[48:49], v[62:63] op_sel:[0,0,1] op_sel_hi:[1,1,0]
	s_nop 0
	v_mov_b32_e32 v81, v49
	s_waitcnt lgkmcnt(0)
	v_pk_add_f32 v[48:49], v[50:51], v[80:81]
	s_nop 0
	v_cvt_pk_bf16_f32 v50, v48, v49
	ds_write_b32 v122, v50 offset:10496
	ds_read_b64 v[50:51], v121 offset:4680
	v_pk_mul_f32 v[62:63], v[78:79], v[48:49]
	s_nop 0
	v_pk_fma_f32 v[80:81], v[52:53], v[48:49], v[62:63] op_sel:[0,0,1] op_sel_hi:[1,1,0] neg_lo:[0,0,1] neg_hi:[0,0,1]
	v_pk_fma_f32 v[48:49], v[52:53], v[48:49], v[62:63] op_sel:[0,0,1] op_sel_hi:[1,1,0]
	s_nop 0
	v_mov_b32_e32 v81, v49
	s_waitcnt lgkmcnt(0)
	v_pk_add_f32 v[48:49], v[50:51], v[80:81]
	s_nop 0
	v_cvt_pk_bf16_f32 v50, v48, v49
	ds_write_b32 v122, v50 offset:10768
	ds_read_b64 v[50:51], v121 offset:5200
	v_pk_mul_f32 v[62:63], v[78:79], v[48:49]
	s_nop 0
	v_pk_fma_f32 v[80:81], v[52:53], v[48:49], v[62:63] op_sel:[0,0,1] op_sel_hi:[1,1,0] neg_lo:[0,0,1] neg_hi:[0,0,1]
	v_pk_fma_f32 v[48:49], v[52:53], v[48:49], v[62:63] op_sel:[0,0,1] op_sel_hi:[1,1,0]
	s_nop 0
	v_mov_b32_e32 v81, v49
	s_waitcnt lgkmcnt(0)
	v_pk_add_f32 v[48:49], v[50:51], v[80:81]
	s_nop 0
	v_cvt_pk_bf16_f32 v50, v48, v49
	ds_write_b32 v122, v50 offset:11040
	ds_read_b64 v[50:51], v121 offset:5720
	v_pk_mul_f32 v[62:63], v[78:79], v[48:49]
	s_nop 0
	v_pk_fma_f32 v[80:81], v[52:53], v[48:49], v[62:63] op_sel:[0,0,1] op_sel_hi:[1,1,0] neg_lo:[0,0,1] neg_hi:[0,0,1]
	v_pk_fma_f32 v[48:49], v[52:53], v[48:49], v[62:63] op_sel:[0,0,1] op_sel_hi:[1,1,0]
	s_nop 0
	v_mov_b32_e32 v81, v49
	s_waitcnt lgkmcnt(0)
	v_pk_add_f32 v[48:49], v[50:51], v[80:81]
	s_nop 0
	v_cvt_pk_bf16_f32 v50, v48, v49
	ds_write_b32 v122, v50 offset:11312
	ds_read_b64 v[50:51], v121 offset:6240
	v_pk_mul_f32 v[62:63], v[78:79], v[48:49]
	s_nop 0
	v_pk_fma_f32 v[80:81], v[52:53], v[48:49], v[62:63] op_sel:[0,0,1] op_sel_hi:[1,1,0] neg_lo:[0,0,1] neg_hi:[0,0,1]
	v_pk_fma_f32 v[48:49], v[52:53], v[48:49], v[62:63] op_sel:[0,0,1] op_sel_hi:[1,1,0]
	s_nop 0
	v_mov_b32_e32 v81, v49
	s_waitcnt lgkmcnt(0)
	v_pk_add_f32 v[48:49], v[50:51], v[80:81]
	s_nop 0
	v_cvt_pk_bf16_f32 v50, v48, v49
	ds_write_b32 v122, v50 offset:11584
	ds_read_b64 v[50:51], v121 offset:6760
	v_pk_mul_f32 v[62:63], v[78:79], v[48:49]
	s_nop 0
	v_pk_fma_f32 v[80:81], v[52:53], v[48:49], v[62:63] op_sel:[0,0,1] op_sel_hi:[1,1,0] neg_lo:[0,0,1] neg_hi:[0,0,1]
	v_pk_fma_f32 v[48:49], v[52:53], v[48:49], v[62:63] op_sel:[0,0,1] op_sel_hi:[1,1,0]
	s_nop 0
	v_mov_b32_e32 v81, v49
	s_waitcnt lgkmcnt(0)
	v_pk_add_f32 v[48:49], v[50:51], v[80:81]
	s_nop 0
	v_cvt_pk_bf16_f32 v50, v48, v49
	ds_write_b32 v122, v50 offset:11856
	ds_read_b64 v[50:51], v121 offset:7280
	v_pk_mul_f32 v[62:63], v[78:79], v[48:49]
	s_nop 0
	v_pk_fma_f32 v[80:81], v[52:53], v[48:49], v[62:63] op_sel:[0,0,1] op_sel_hi:[1,1,0] neg_lo:[0,0,1] neg_hi:[0,0,1]
	v_pk_fma_f32 v[48:49], v[52:53], v[48:49], v[62:63] op_sel:[0,0,1] op_sel_hi:[1,1,0]
	s_nop 0
	v_mov_b32_e32 v81, v49
	s_waitcnt lgkmcnt(0)
	v_pk_add_f32 v[48:49], v[50:51], v[80:81]
	s_nop 0
	v_cvt_pk_bf16_f32 v50, v48, v49
	ds_write_b32 v122, v50 offset:12128
	ds_read_b64 v[50:51], v121 offset:7800
	v_pk_mul_f32 v[62:63], v[78:79], v[48:49]
	s_nop 0
	v_pk_fma_f32 v[80:81], v[52:53], v[48:49], v[62:63] op_sel:[0,0,1] op_sel_hi:[1,1,0] neg_lo:[0,0,1] neg_hi:[0,0,1]
	v_pk_fma_f32 v[48:49], v[52:53], v[48:49], v[62:63] op_sel:[0,0,1] op_sel_hi:[1,1,0]
	v_lshl_add_u64 v[62:63], v[58:59], 0, s[4:5]
	v_mov_b32_e32 v81, v49
	s_waitcnt lgkmcnt(0)
	v_pk_add_f32 v[80:81], v[50:51], v[80:81]
	s_add_u32 s4, s4, 0x2000
	v_cvt_pk_bf16_f32 v48, v80, v81
	ds_write_b32 v122, v48 offset:12400
	s_waitcnt lgkmcnt(0)
	ds_read_b128 v[48:51], v123 offset:8320
	ds_read_b128 v[84:87], v123 offset:8384
	s_waitcnt lgkmcnt(1)
	v_mfma_f32_16x16x32_bf16 v[48:51], v[48:51], v[32:35], 0
	s_addc_u32 s5, s5, 0
	s_cmpk_lg_u32 s4, 0x8000
	v_mov_b32_e32 v82, v81
	s_waitcnt lgkmcnt(0)
	v_mfma_f32_16x16x32_bf16 v[48:51], v[84:87], v[36:39], v[48:51]
	ds_read_b128 v[84:87], v123 offset:8448
	s_waitcnt lgkmcnt(0)
	v_mfma_f32_16x16x32_bf16 v[48:51], v[84:87], v[40:43], v[48:51]
	ds_read_b128 v[84:87], v123 offset:8512
	s_waitcnt lgkmcnt(0)
	v_mfma_f32_16x16x32_bf16 v[48:51], v[84:87], v[44:47], v[48:51]
	v_add_co_u32_e32 v84, vcc, s6, v62
	s_mov_b32 s6, 0xa800000
	s_nop 0
	v_addc_co_u32_e32 v85, vcc, 0, v63, vcc
	v_add_co_u32_e32 v62, vcc, s6, v62
	s_waitcnt vmcnt(0)
	v_lshlrev_b32_e32 v61, 16, v92
	v_fma_f32 v48, v60, v61, v48
	v_bfe_u32 v61, v48, 16, 1
	v_add3_u32 v48, v48, v61, s52
	v_addc_co_u32_e32 v63, vcc, 0, v63, vcc
	global_store_short_d16_hi v[62:63], v48, off
	v_lshlrev_b32_e32 v48, 16, v93
	v_fma_f32 v48, v60, v48, v49
	v_bfe_u32 v49, v48, 16, 1
	v_add3_u32 v48, v48, v49, s52
	global_store_short_d16_hi v[62:63], v48, off offset:512
	v_lshlrev_b32_e32 v48, 16, v94
	v_fma_f32 v48, v60, v48, v50
	v_bfe_u32 v49, v48, 16, 1
	v_add3_u32 v48, v48, v49, s52
	global_store_short_d16_hi v[62:63], v48, off offset:1024
	v_lshlrev_b32_e32 v48, 16, v95
	v_fmac_f32_e32 v51, v60, v48
	v_bfe_u32 v48, v51, 16, 1
	v_add3_u32 v48, v51, v48, s52
	global_store_short_d16_hi v[62:63], v48, off offset:1536
	s_waitcnt lgkmcnt(0)
	s_cbranch_scc0 .LBB0_497

; __device__ __forceinline__ unsigned xb_ld(unsigned* p)              { return __hip_atomic_load(p, __ATOMIC_RELAXED, __HIP_MEMORY_SCOPE_AGENT); }
; __device__ __forceinline__ unsigned xb_add(unsigned* p, unsigned v) { return __hip_atomic_fetch_add(p, v, __ATOMIC_RELAXED, __HIP_MEMORY_SCOPE_AGENT); }
; #define XB_SPIN(cond, bar) do { unsigned _sp = 0; while (cond) { __builtin_amdgcn_s_sleep(1); \
;     if ((++_sp & 255u) == 0u) { if (xb_ld(&(bar)[XB_TMO])) break; if (_sp > XB_SPIN_CAP) { atomicAdd(&(bar)[XB_TMO], 1u); break; } } } } while (0)
; __device__ __forceinline__ void xcd_barrier(const XcdBarrier& b) {
;     asm volatile("s_waitcnt vmcnt(0)" ::: "memory");
;     __syncthreads();
;     if (threadIdx.x == 0) {
;         unsigned* bar = b.bar;
;         unsigned bx = (unsigned)__builtin_amdgcn_readfirstlane((int)b.x); asm volatile("" : "+s"(bx));
;         __builtin_amdgcn_s_waitcnt(0);
;         unsigned nloc = b.st[0], nx = b.st[1];
;         if (nloc == 0u) { xcd_barrier_complete(bar, bx, nloc, nx); b.st[0] = nloc; b.st[1] = nx; }
;         const unsigned old = xb_add(&bar[XB_XSUB(bx)], 1u);
;         const unsigned gen = old / nloc;
;         if (old + 1u == (gen + 1u) * nloc) {
;             __builtin_amdgcn_fence(__ATOMIC_RELEASE, "agent");
;             asm volatile("s_waitcnt vmcnt(0)" ::: "memory");
;             const unsigned og = xb_add(&bar[XB_TOP], 1u);
;             const unsigned tg = og / nx;
;             if (og + 1u == (tg + 1u) * nx) xb_add(&bar[XB_TOPGEN], 1u);
;             else XB_SPIN(xb_ld(&bar[XB_TOPGEN]) == tg, bar);
;             __builtin_amdgcn_fence(__ATOMIC_ACQUIRE, "agent");
;             xb_add(&bar[XB_XGEN(bx)], 1u);
;             asm volatile("s_waitcnt vmcnt(0)" ::: "memory");
.LBB0_832:
	s_andn2_saveexec_b64 s[2:3], s[2:3]
	s_cbranch_execz .LBB0_852
	s_mov_b64 s[2:3], exec
	v_mov_b32_e32 v1, 0x20208
	ds_read_b32 v1, v1
	s_waitcnt lgkmcnt(0)
	v_readfirstlane_b32 s101, v1
	s_nop 3
	s_cmp_lg_u32 s101, 0
	s_cbranch_scc1 .LBB0_849
	buffer_wbl2 sc1
	s_waitcnt lgkmcnt(0)
	s_waitcnt vmcnt(0)
	v_mbcnt_lo_u32_b32 v1, s2, 0
	v_mbcnt_hi_u32_b32 v1, s3, v1
	v_cmp_eq_u32_e32 vcc, 0, v1
	s_and_saveexec_b64 s[4:5], vcc
	s_cbranch_execz .LBB0_835
	s_bcnt1_i32_b64 s2, s[2:3]
	v_mov_b32_e32 v2, s2
	v_readlane_b32 s2, v254, 24
	v_readlane_b32 s3, v254, 25
	s_nop 4
	global_atomic_add v2, v157, v2, s[2:3] sc0

; __global__ void __launch_bounds__(NWAVES * 64, 2) fwd_kernel(KArgs a) {
	.amdhsa_kernel _Z10fwd_kernel5KArgs
		.amdhsa_group_segment_fixed_size 0
		.amdhsa_private_segment_fixed_size 0
		.amdhsa_kernarg_size 536
		.amdhsa_user_sgpr_count 2
		.amdhsa_user_sgpr_dispatch_ptr 0
		.amdhsa_user_sgpr_queue_ptr 0
		.amdhsa_user_sgpr_kernarg_segment_ptr 1
		.amdhsa_user_sgpr_dispatch_id 0
		.amdhsa_user_sgpr_kernarg_preload_length 0
		.amdhsa_user_sgpr_kernarg_preload_offset 0
		.amdhsa_user_sgpr_private_segment_size 0
		.amdhsa_uses_dynamic_stack 0
		.amdhsa_enable_private_segment 0
		.amdhsa_system_sgpr_workgroup_id_x 1
		.amdhsa_system_sgpr_workgroup_id_y 0
		.amdhsa_system_sgpr_workgroup_id_z 0
		.amdhsa_system_sgpr_workgroup_info 0
		.amdhsa_system_vgpr_workitem_id 2
		.amdhsa_next_free_vgpr 255
		.amdhsa_next_free_sgpr 102
		.amdhsa_accum_offset 256
		.amdhsa_reserve_vcc 1
		.amdhsa_float_round_mode_32 0
		.amdhsa_float_round_mode_16_64 0
		.amdhsa_float_denorm_mode_32 3
		.amdhsa_float_denorm_mode_16_64 3
		.amdhsa_dx10_clamp 1
		.amdhsa_ieee_mode 1
		.amdhsa_fp16_overflow 0
		.amdhsa_tg_split 0
		.amdhsa_exception_fp_ieee_invalid_op 0
		.amdhsa_exception_fp_denorm_src 0
		.amdhsa_exception_fp_ieee_div_zero 0
		.amdhsa_exception_fp_ieee_overflow 0
		.amdhsa_exception_fp_ieee_underflow 0
		.amdhsa_exception_fp_ieee_inexact 0
		.amdhsa_exception_int_div_zero 0
	.end_amdhsa_kernel

; __global__ void __launch_bounds__(NWAVES * 64, 2) fwd_kernel(KArgs a) {
amdhsa.kernels:
  - .agpr_count:     0
    .args:
      - .offset:         0
        .size:           280
        .value_kind:     by_value
      - .offset:         280
        .size:           4
        .value_kind:     hidden_block_count_x
      - .offset:         284
        .size:           4
        .value_kind:     hidden_block_count_y
      - .offset:         288
        .size:           4
        .value_kind:     hidden_block_count_z
      - .offset:         292
        .size:           2
        .value_kind:     hidden_group_size_x
      - .offset:         294
        .size:           2
        .value_kind:     hidden_group_size_y
      - .offset:         296
        .size:           2
        .value_kind:     hidden_group_size_z
      - .offset:         298
        .size:           2
        .value_kind:     hidden_remainder_x
      - .offset:         300
        .size:           2
        .value_kind:     hidden_remainder_y
      - .offset:         302
        .size:           2
        .value_kind:     hidden_remainder_z
      - .offset:         320
        .size:           8
        .value_kind:     hidden_global_offset_x
      - .offset:         328
        .size:           8
        .value_kind:     hidden_global_offset_y
      - .offset:         336
        .size:           8
        .value_kind:     hidden_global_offset_z
      - .offset:         344
        .size:           2
        .value_kind:     hidden_grid_dims
      - .offset:         368
        .size:           8
        .value_kind:     hidden_multigrid_sync_arg
      - .offset:         400
        .size:           4
        .value_kind:     hidden_dynamic_lds_size
    .group_segment_fixed_size: 0
    .kernarg_segment_align: 8
    .kernarg_segment_size: 536
    .language:       OpenCL C
    .language_version:
      - 2
      - 0
    .max_flat_workgroup_size: 512
    .name:           _Z10fwd_kernel5KArgs
    .private_segment_fixed_size: 0
    .sgpr_count:     108
    .sgpr_spill_count: 115
    .symbol:         _Z10fwd_kernel5KArgs.kd
    .uniform_work_group_size: 1
    .uses_dynamic_stack: false
    .vgpr_count:     255
    .vgpr_spill_count: 0
    .wavefront_size: 64
